# fox_prep tile body de-serialized: 8 V loads + 16 q/k loads issued up front (counted vmcnt), q/k row reductions by DPP instead of 4 ds_bpermute round trips, norm weights loaded once per tile; bit-ident
# speedup vs baseline: 1.0050x; 1.0050x over previous
; __device__ __forceinline__ int bid_fresh() { int t = blockIdx.x; asm volatile("" : "+s"(t)); return t; }
; __device__ __forceinline__ int gdim_fresh() { int t = gridDim.x; asm volatile("" : "+s"(t)); return t; }
; __device__ __forceinline__ void fox_prep(ArgsP a, int j, unsigned char* lds) {
;     ...
;     for (int tile = bid_fresh(); tile < 512; tile += gdim_fresh()) {
;         const int b = tile >> 6, tb = tile & 63; const size_t r0 = (size_t)b * T_ + tb * 64;
;         __syncthreads();
; #pragma unroll
;         for (int k = 0; k < 8; ++k) { const int id = tid + 512 * k, r = id >> 6, c = id & 63;
;             const u32x4 w = *(const u32x4*)(BIG + BIGX(r0 + r, 3072 + c * 8));
;             unsigned* dst = (unsigned*)(lds + r * 1028 + c * 16); dst[0] = w.x; dst[1] = w.y; dst[2] = w.z; dst[3] = w.w; }
; #pragma unroll 2
;         for (int p = 0; p < 16; ++p) { const int grp = p * 32 + (tid >> 4), sub = tid & 15; const int r = grp >> 3, which = (grp >> 2) & 1, h = grp & 3;
;             bf16* ptr = BIG + BIGX(r0 + r, 2048 + which * 512 + h * 128 + sub * 8);
;             const u32x4 w = *(const u32x4*)ptr; float v[8];
.LBB0_783:
	s_ashr_i32 s4, s8, 6
	s_ashr_i32 s5, s4, 31
	s_lshl_b64 s[6:7], s[4:5], 12
	s_lshl_b32 s5, s8, 6
	s_and_b32 s5, s5, 0xfc0
	s_or_b32 s6, s6, s5
	v_lshl_add_u64 v[54:55], s[6:7], 0, v[2:3]
	v_lshl_add_u64 v[32:33], v[54:55], 0, v[12:13]
	v_lshlrev_b64 v[32:33], 9, v[32:33]
	v_lshl_add_u64 v[32:33], v[4:5], 0, v[32:33]
	s_barrier
	v_lshl_add_u64 v[76:77], v[54:55], 0, v[12:13]
	v_lshlrev_b64 v[76:77], 9, v[76:77]
	v_lshl_add_u64 v[76:77], v[4:5], 0, v[76:77]
	global_load_dwordx4 v[112:115], v[76:77], off
	v_lshl_add_u64 v[76:77], v[54:55], 0, v[14:15]
	v_lshlrev_b64 v[76:77], 9, v[76:77]
	v_lshl_add_u64 v[76:77], v[4:5], 0, v[76:77]
	global_load_dwordx4 v[116:119], v[76:77], off
	v_lshl_add_u64 v[76:77], v[54:55], 0, v[16:17]
	v_lshlrev_b64 v[76:77], 9, v[76:77]
	v_lshl_add_u64 v[76:77], v[4:5], 0, v[76:77]
	global_load_dwordx4 v[120:123], v[76:77], off
	v_lshl_add_u64 v[76:77], v[54:55], 0, v[18:19]
	v_lshlrev_b64 v[76:77], 9, v[76:77]
	v_lshl_add_u64 v[76:77], v[4:5], 0, v[76:77]
	global_load_dwordx4 v[124:127], v[76:77], off
	v_lshl_add_u64 v[76:77], v[54:55], 0, v[20:21]
	v_lshlrev_b64 v[76:77], 9, v[76:77]
	v_lshl_add_u64 v[76:77], v[4:5], 0, v[76:77]
	global_load_dwordx4 v[128:131], v[76:77], off
	v_lshl_add_u64 v[76:77], v[54:55], 0, v[22:23]
	v_lshlrev_b64 v[76:77], 9, v[76:77]
	v_lshl_add_u64 v[76:77], v[4:5], 0, v[76:77]
	global_load_dwordx4 v[132:135], v[76:77], off
	v_lshl_add_u64 v[76:77], v[54:55], 0, v[24:25]
	v_lshlrev_b64 v[76:77], 9, v[76:77]
	v_lshl_add_u64 v[76:77], v[4:5], 0, v[76:77]
	global_load_dwordx4 v[136:139], v[76:77], off
	v_lshl_add_u64 v[76:77], v[54:55], 0, v[26:27]
	v_lshlrev_b64 v[76:77], 9, v[76:77]
	v_lshl_add_u64 v[76:77], v[4:5], 0, v[76:77]
	global_load_dwordx4 v[140:143], v[76:77], off
	v_lshl_add_u64 v[32:33], s[6:7], 0, v[6:7]
	v_add_u32_e32 v31, 0, v36
	v_ashrrev_i32_e32 v34, 3, v31
	v_ashrrev_i32_e32 v35, 31, v34
	v_lshl_add_u64 v[34:35], v[32:33], 0, v[34:35]
	v_lshlrev_b64 v[34:35], 9, v[34:35]
	v_lshl_add_u64 v[34:35], v[8:9], 0, v[34:35]
	global_load_dwordx4 v[188:191], v[34:35], off
	v_add_u32_e32 v31, 32, v36
	v_ashrrev_i32_e32 v34, 3, v31
	v_ashrrev_i32_e32 v35, 31, v34
	v_lshl_add_u64 v[34:35], v[32:33], 0, v[34:35]
	v_lshlrev_b64 v[34:35], 9, v[34:35]
	v_lshl_add_u64 v[34:35], v[8:9], 0, v[34:35]
	global_load_dwordx4 v[192:195], v[34:35], off
	v_add_u32_e32 v31, 64, v36
	v_ashrrev_i32_e32 v34, 3, v31
	v_ashrrev_i32_e32 v35, 31, v34
	v_lshl_add_u64 v[34:35], v[32:33], 0, v[34:35]
	v_lshlrev_b64 v[34:35], 9, v[34:35]
	v_lshl_add_u64 v[34:35], v[8:9], 0, v[34:35]
	global_load_dwordx4 v[196:199], v[34:35], off
	v_add_u32_e32 v31, 0x60, v36
	v_ashrrev_i32_e32 v34, 3, v31
	v_ashrrev_i32_e32 v35, 31, v34
	v_lshl_add_u64 v[34:35], v[32:33], 0, v[34:35]
	v_lshlrev_b64 v[34:35], 9, v[34:35]
	v_lshl_add_u64 v[34:35], v[8:9], 0, v[34:35]
	global_load_dwordx4 v[200:203], v[34:35], off
	v_add_u32_e32 v31, 0x80, v36
	v_ashrrev_i32_e32 v34, 3, v31
	v_ashrrev_i32_e32 v35, 31, v34
	v_lshl_add_u64 v[34:35], v[32:33], 0, v[34:35]
	v_lshlrev_b64 v[34:35], 9, v[34:35]
	v_lshl_add_u64 v[34:35], v[8:9], 0, v[34:35]
	global_load_dwordx4 v[204:207], v[34:35], off
	v_add_u32_e32 v31, 0xa0, v36
	v_ashrrev_i32_e32 v34, 3, v31
	v_ashrrev_i32_e32 v35, 31, v34
	v_lshl_add_u64 v[34:35], v[32:33], 0, v[34:35]
	v_lshlrev_b64 v[34:35], 9, v[34:35]
	v_lshl_add_u64 v[34:35], v[8:9], 0, v[34:35]
	global_load_dwordx4 v[208:211], v[34:35], off
	v_add_u32_e32 v31, 0xc0, v36
	v_ashrrev_i32_e32 v34, 3, v31
	v_ashrrev_i32_e32 v35, 31, v34
	v_lshl_add_u64 v[34:35], v[32:33], 0, v[34:35]
	v_lshlrev_b64 v[34:35], 9, v[34:35]
	v_lshl_add_u64 v[34:35], v[8:9], 0, v[34:35]
	global_load_dwordx4 v[212:215], v[34:35], off
	v_add_u32_e32 v31, 0xe0, v36
	v_ashrrev_i32_e32 v34, 3, v31
	v_ashrrev_i32_e32 v35, 31, v34
	v_lshl_add_u64 v[34:35], v[32:33], 0, v[34:35]
	v_lshlrev_b64 v[34:35], 9, v[34:35]
	v_lshl_add_u64 v[34:35], v[8:9], 0, v[34:35]
	global_load_dwordx4 v[216:219], v[34:35], off
	global_load_dwordx4 v[220:223], v[10:11], off
	global_load_dwordx4 v[148:151], v[10:11], off offset:16
	s_waitcnt vmcnt(17)
	ds_write2_b32 v45, v112, v113 offset1:1
	ds_write2_b32 v45, v114, v115 offset0:2 offset1:3
	v_add_u32_e32 v31, 0x100, v36
	v_ashrrev_i32_e32 v34, 3, v31
	v_ashrrev_i32_e32 v35, 31, v34
	v_lshl_add_u64 v[34:35], v[32:33], 0, v[34:35]
	v_lshlrev_b64 v[34:35], 9, v[34:35]
	v_lshl_add_u64 v[34:35], v[8:9], 0, v[34:35]
	s_nop 0
	global_load_dwordx4 v[112:115], v[34:35], off
	s_waitcnt vmcnt(17)
	ds_write2_b32 v46, v116, v117 offset1:1
	ds_write2_b32 v46, v118, v119 offset0:2 offset1:3
	v_add_u32_e32 v31, 0x120, v36
	v_ashrrev_i32_e32 v34, 3, v31
	v_ashrrev_i32_e32 v35, 31, v34
	v_lshl_add_u64 v[34:35], v[32:33], 0, v[34:35]
	v_lshlrev_b64 v[34:35], 9, v[34:35]
	v_lshl_add_u64 v[34:35], v[8:9], 0, v[34:35]
	s_nop 0
	global_load_dwordx4 v[116:119], v[34:35], off
	s_waitcnt vmcnt(17)
	ds_write2_b32 v47, v120, v121 offset1:1
	ds_write2_b32 v47, v122, v123 offset0:2 offset1:3
	v_add_u32_e32 v31, 0x140, v36
	v_ashrrev_i32_e32 v34, 3, v31
	v_ashrrev_i32_e32 v35, 31, v34
	v_lshl_add_u64 v[34:35], v[32:33], 0, v[34:35]
	v_lshlrev_b64 v[34:35], 9, v[34:35]
	v_lshl_add_u64 v[34:35], v[8:9], 0, v[34:35]
	s_nop 0
	global_load_dwordx4 v[120:123], v[34:35], off
	s_waitcnt vmcnt(17)
	ds_write2_b32 v48, v124, v125 offset1:1
	ds_write2_b32 v48, v126, v127 offset0:2 offset1:3
	v_add_u32_e32 v31, 0x160, v36
	v_ashrrev_i32_e32 v34, 3, v31
	v_ashrrev_i32_e32 v35, 31, v34
	v_lshl_add_u64 v[34:35], v[32:33], 0, v[34:35]
	v_lshlrev_b64 v[34:35], 9, v[34:35]
	v_lshl_add_u64 v[34:35], v[8:9], 0, v[34:35]
	s_nop 0
	global_load_dwordx4 v[124:127], v[34:35], off
	s_waitcnt vmcnt(17)
; __device__ __forceinline__ float bflo(unsigned u) { return __uint_as_float(u << 16); }
; __device__ __forceinline__ float bfhi(unsigned u) { return __uint_as_float(u & 0xffff0000u); }
; __device__ __forceinline__ void fox_prep(ArgsP a, int j, unsigned char* lds) {
;     ...
;         for (int k = 0; k < 8; ++k) { const int id = tid + 512 * k, r = id >> 6, c = id & 63;
;             const u32x4 w = *(const u32x4*)(BIG + BIGX(r0 + r, 3072 + c * 8));
;             unsigned* dst = (unsigned*)(lds + r * 1028 + c * 16); dst[0] = w.x; dst[1] = w.y; dst[2] = w.z; dst[3] = w.w; }
; #pragma unroll 2
;         for (int p = 0; p < 16; ++p) { const int grp = p * 32 + (tid >> 4), sub = tid & 15; const int r = grp >> 3, which = (grp >> 2) & 1, h = grp & 3;
;             bf16* ptr = BIG + BIGX(r0 + r, 2048 + which * 512 + h * 128 + sub * 8);
;             const u32x4 w = *(const u32x4*)ptr; float v[8];
; #pragma unroll
;             for (int e = 0; e < 4; ++e) { v[2 * e] = bflo(w[e]); v[2 * e + 1] = bfhi(w[e]); }
;             float ss = 0.f;
; #pragma unroll
;             for (int e = 0; e < 8; ++e) ss += v[e] * v[e];
	ds_write2_b32 v49, v128, v129 offset1:1
	ds_write2_b32 v49, v130, v131 offset0:2 offset1:3
	v_add_u32_e32 v31, 0x180, v36
	v_ashrrev_i32_e32 v34, 3, v31
	v_ashrrev_i32_e32 v35, 31, v34
	v_lshl_add_u64 v[34:35], v[32:33], 0, v[34:35]
	v_lshlrev_b64 v[34:35], 9, v[34:35]
	v_lshl_add_u64 v[34:35], v[8:9], 0, v[34:35]
	s_nop 0
	global_load_dwordx4 v[128:131], v[34:35], off
	s_waitcnt vmcnt(17)
	ds_write2_b32 v50, v132, v133 offset1:1
	ds_write2_b32 v50, v134, v135 offset0:2 offset1:3
	v_add_u32_e32 v31, 0x1a0, v36
	v_ashrrev_i32_e32 v34, 3, v31
	v_ashrrev_i32_e32 v35, 31, v34
	v_lshl_add_u64 v[34:35], v[32:33], 0, v[34:35]
	v_lshlrev_b64 v[34:35], 9, v[34:35]
	v_lshl_add_u64 v[34:35], v[8:9], 0, v[34:35]
	s_nop 0
	global_load_dwordx4 v[132:135], v[34:35], off
	s_waitcnt vmcnt(17)
	ds_write2_b32 v51, v136, v137 offset1:1
	ds_write2_b32 v51, v138, v139 offset0:2 offset1:3
	v_add_u32_e32 v31, 0x1c0, v36
	v_ashrrev_i32_e32 v34, 3, v31
	v_ashrrev_i32_e32 v35, 31, v34
	v_lshl_add_u64 v[34:35], v[32:33], 0, v[34:35]
	v_lshlrev_b64 v[34:35], 9, v[34:35]
	v_lshl_add_u64 v[34:35], v[8:9], 0, v[34:35]
	s_nop 0
	global_load_dwordx4 v[136:139], v[34:35], off
	s_waitcnt vmcnt(17)
	ds_write2_b32 v52, v140, v141 offset1:1
	ds_write2_b32 v52, v142, v143 offset0:2 offset1:3
	v_add_u32_e32 v31, 0x1e0, v36
	v_ashrrev_i32_e32 v34, 3, v31
	v_ashrrev_i32_e32 v35, 31, v34
	v_lshl_add_u64 v[34:35], v[32:33], 0, v[34:35]
	v_lshlrev_b64 v[34:35], 9, v[34:35]
	v_lshl_add_u64 v[34:35], v[8:9], 0, v[34:35]
	s_nop 0
	global_load_dwordx4 v[140:143], v[34:35], off
	s_waitcnt vmcnt(8)
	v_lshlrev_b32_e32 v72, 16, v188
	v_and_b32_e32 v73, 0xffff0000, v188
	v_pk_mul_f32 v[74:75], v[72:73], v[72:73]
	s_nop 0
	v_add_f32_e32 v56, v74, v75
	v_lshlrev_b32_e32 v72, 16, v189
	v_and_b32_e32 v73, 0xffff0000, v189
	v_pk_mul_f32 v[74:75], v[72:73], v[72:73]
	s_nop 0
	v_add_f32_e32 v56, v74, v56
	v_add_f32_e32 v56, v75, v56
	v_lshlrev_b32_e32 v72, 16, v190
	v_and_b32_e32 v73, 0xffff0000, v190
	v_pk_mul_f32 v[74:75], v[72:73], v[72:73]
	s_nop 0
	v_add_f32_e32 v56, v74, v56
	v_add_f32_e32 v56, v75, v56
	v_lshlrev_b32_e32 v72, 16, v191
	v_and_b32_e32 v73, 0xffff0000, v191
	v_pk_mul_f32 v[74:75], v[72:73], v[72:73]
	s_nop 0
	v_add_f32_e32 v56, v74, v56
	v_add_f32_e32 v56, v75, v56
	v_lshlrev_b32_e32 v72, 16, v192
	v_and_b32_e32 v73, 0xffff0000, v192
	v_pk_mul_f32 v[74:75], v[72:73], v[72:73]
	s_nop 0
	v_add_f32_e32 v57, v74, v75
	v_lshlrev_b32_e32 v72, 16, v193
	v_and_b32_e32 v73, 0xffff0000, v193
	v_pk_mul_f32 v[74:75], v[72:73], v[72:73]
	s_nop 0
	v_add_f32_e32 v57, v74, v57
	v_add_f32_e32 v57, v75, v57
	v_lshlrev_b32_e32 v72, 16, v194
	v_and_b32_e32 v73, 0xffff0000, v194
	v_pk_mul_f32 v[74:75], v[72:73], v[72:73]
	s_nop 0
	v_add_f32_e32 v57, v74, v57
	v_add_f32_e32 v57, v75, v57
	v_lshlrev_b32_e32 v72, 16, v195
	v_and_b32_e32 v73, 0xffff0000, v195
	v_pk_mul_f32 v[74:75], v[72:73], v[72:73]
	s_nop 0
	v_add_f32_e32 v57, v74, v57
	v_add_f32_e32 v57, v75, v57
	v_lshlrev_b32_e32 v72, 16, v196
	v_and_b32_e32 v73, 0xffff0000, v196
	v_pk_mul_f32 v[74:75], v[72:73], v[72:73]
	s_nop 0
	v_add_f32_e32 v58, v74, v75
	v_lshlrev_b32_e32 v72, 16, v197
	v_and_b32_e32 v73, 0xffff0000, v197
	v_pk_mul_f32 v[74:75], v[72:73], v[72:73]
	s_nop 0
	v_add_f32_e32 v58, v74, v58
	v_add_f32_e32 v58, v75, v58
	v_lshlrev_b32_e32 v72, 16, v198
	v_and_b32_e32 v73, 0xffff0000, v198
	v_pk_mul_f32 v[74:75], v[72:73], v[72:73]
	s_nop 0
	v_add_f32_e32 v58, v74, v58
	v_add_f32_e32 v58, v75, v58
	v_lshlrev_b32_e32 v72, 16, v199
	v_and_b32_e32 v73, 0xffff0000, v199
	v_pk_mul_f32 v[74:75], v[72:73], v[72:73]
	s_nop 0
	v_add_f32_e32 v58, v74, v58
	v_add_f32_e32 v58, v75, v58
	v_lshlrev_b32_e32 v72, 16, v200
	v_and_b32_e32 v73, 0xffff0000, v200
	v_pk_mul_f32 v[74:75], v[72:73], v[72:73]
	s_nop 0
	v_add_f32_e32 v59, v74, v75
	v_lshlrev_b32_e32 v72, 16, v201
	v_and_b32_e32 v73, 0xffff0000, v201
	v_pk_mul_f32 v[74:75], v[72:73], v[72:73]
	s_nop 0
	v_add_f32_e32 v59, v74, v59
	v_add_f32_e32 v59, v75, v59
	v_lshlrev_b32_e32 v72, 16, v202
	v_and_b32_e32 v73, 0xffff0000, v202
	v_pk_mul_f32 v[74:75], v[72:73], v[72:73]
	s_nop 0
	v_add_f32_e32 v59, v74, v59
	v_add_f32_e32 v59, v75, v59
	v_lshlrev_b32_e32 v72, 16, v203
	v_and_b32_e32 v73, 0xffff0000, v203
	v_pk_mul_f32 v[74:75], v[72:73], v[72:73]
	s_nop 0
	v_add_f32_e32 v59, v74, v59
	v_add_f32_e32 v59, v75, v59
	v_lshlrev_b32_e32 v72, 16, v204
	v_and_b32_e32 v73, 0xffff0000, v204
	v_pk_mul_f32 v[74:75], v[72:73], v[72:73]
	s_nop 0
	v_add_f32_e32 v60, v74, v75
	v_lshlrev_b32_e32 v72, 16, v205
	v_and_b32_e32 v73, 0xffff0000, v205
	v_pk_mul_f32 v[74:75], v[72:73], v[72:73]
	s_nop 0
	v_add_f32_e32 v60, v74, v60
	v_add_f32_e32 v60, v75, v60
	v_lshlrev_b32_e32 v72, 16, v206
	v_and_b32_e32 v73, 0xffff0000, v206
	v_pk_mul_f32 v[74:75], v[72:73], v[72:73]
	s_nop 0
	v_add_f32_e32 v60, v74, v60
	v_add_f32_e32 v60, v75, v60
	v_lshlrev_b32_e32 v72, 16, v207
	v_and_b32_e32 v73, 0xffff0000, v207
	v_pk_mul_f32 v[74:75], v[72:73], v[72:73]
	s_nop 0
	v_add_f32_e32 v60, v74, v60
	v_add_f32_e32 v60, v75, v60
	v_lshlrev_b32_e32 v72, 16, v208
	v_and_b32_e32 v73, 0xffff0000, v208
	v_pk_mul_f32 v[74:75], v[72:73], v[72:73]
	s_nop 0
	v_add_f32_e32 v61, v74, v75
	v_lshlrev_b32_e32 v72, 16, v209
	v_and_b32_e32 v73, 0xffff0000, v209
	v_pk_mul_f32 v[74:75], v[72:73], v[72:73]
	s_nop 0
	v_add_f32_e32 v61, v74, v61
	v_add_f32_e32 v61, v75, v61
	v_lshlrev_b32_e32 v72, 16, v210
	v_and_b32_e32 v73, 0xffff0000, v210
	v_pk_mul_f32 v[74:75], v[72:73], v[72:73]
	s_nop 0
	v_add_f32_e32 v61, v74, v61
	v_add_f32_e32 v61, v75, v61
	v_lshlrev_b32_e32 v72, 16, v211
	v_and_b32_e32 v73, 0xffff0000, v211
	v_pk_mul_f32 v[74:75], v[72:73], v[72:73]
; __device__ __forceinline__ void fox_prep(ArgsP a, int j, unsigned char* lds) {
;     ...
;             float ss = 0.f;
; #pragma unroll
;             for (int e = 0; e < 8; ++e) ss += v[e] * v[e];
;             ss += __shfl_xor(ss, 1); ss += __shfl_xor(ss, 2); ss += __shfl_xor(ss, 4); ss += __shfl_xor(ss, 8);
;             const float rs = rsqrtf(ss * (1.f / 128.f) + EPS_) * (which == 0 ? 0.12751743f : 1.f);
	s_nop 0
	v_add_f32_e32 v61, v74, v61
	v_add_f32_e32 v61, v75, v61
	v_lshlrev_b32_e32 v72, 16, v212
	v_and_b32_e32 v73, 0xffff0000, v212
	v_pk_mul_f32 v[74:75], v[72:73], v[72:73]
	s_nop 0
	v_add_f32_e32 v62, v74, v75
	v_lshlrev_b32_e32 v72, 16, v213
	v_and_b32_e32 v73, 0xffff0000, v213
	v_pk_mul_f32 v[74:75], v[72:73], v[72:73]
	s_nop 0
	v_add_f32_e32 v62, v74, v62
	v_add_f32_e32 v62, v75, v62
	v_lshlrev_b32_e32 v72, 16, v214
	v_and_b32_e32 v73, 0xffff0000, v214
	v_pk_mul_f32 v[74:75], v[72:73], v[72:73]
	s_nop 0
	v_add_f32_e32 v62, v74, v62
	v_add_f32_e32 v62, v75, v62
	v_lshlrev_b32_e32 v72, 16, v215
	v_and_b32_e32 v73, 0xffff0000, v215
	v_pk_mul_f32 v[74:75], v[72:73], v[72:73]
	s_nop 0
	v_add_f32_e32 v62, v74, v62
	v_add_f32_e32 v62, v75, v62
	v_lshlrev_b32_e32 v72, 16, v216
	v_and_b32_e32 v73, 0xffff0000, v216
	v_pk_mul_f32 v[74:75], v[72:73], v[72:73]
	s_nop 0
	v_add_f32_e32 v63, v74, v75
	v_lshlrev_b32_e32 v72, 16, v217
	v_and_b32_e32 v73, 0xffff0000, v217
	v_pk_mul_f32 v[74:75], v[72:73], v[72:73]
	s_nop 0
	v_add_f32_e32 v63, v74, v63
	v_add_f32_e32 v63, v75, v63
	v_lshlrev_b32_e32 v72, 16, v218
	v_and_b32_e32 v73, 0xffff0000, v218
	v_pk_mul_f32 v[74:75], v[72:73], v[72:73]
	s_nop 0
	v_add_f32_e32 v63, v74, v63
	v_add_f32_e32 v63, v75, v63
	v_lshlrev_b32_e32 v72, 16, v219
	v_and_b32_e32 v73, 0xffff0000, v219
	v_pk_mul_f32 v[74:75], v[72:73], v[72:73]
	s_nop 0
	v_add_f32_e32 v63, v74, v63
	v_add_f32_e32 v63, v75, v63
	v_add_f32_dpp v56, v56, v56 quad_perm:[1,0,3,2] row_mask:0xf bank_mask:0xf
	v_add_f32_dpp v57, v57, v57 quad_perm:[1,0,3,2] row_mask:0xf bank_mask:0xf
	v_add_f32_dpp v58, v58, v58 quad_perm:[1,0,3,2] row_mask:0xf bank_mask:0xf
	v_add_f32_dpp v59, v59, v59 quad_perm:[1,0,3,2] row_mask:0xf bank_mask:0xf
	v_add_f32_dpp v60, v60, v60 quad_perm:[1,0,3,2] row_mask:0xf bank_mask:0xf
	v_add_f32_dpp v61, v61, v61 quad_perm:[1,0,3,2] row_mask:0xf bank_mask:0xf
	v_add_f32_dpp v62, v62, v62 quad_perm:[1,0,3,2] row_mask:0xf bank_mask:0xf
	v_add_f32_dpp v63, v63, v63 quad_perm:[1,0,3,2] row_mask:0xf bank_mask:0xf
	v_add_f32_dpp v56, v56, v56 quad_perm:[2,3,0,1] row_mask:0xf bank_mask:0xf
	v_add_f32_dpp v57, v57, v57 quad_perm:[2,3,0,1] row_mask:0xf bank_mask:0xf
	v_add_f32_dpp v58, v58, v58 quad_perm:[2,3,0,1] row_mask:0xf bank_mask:0xf
	v_add_f32_dpp v59, v59, v59 quad_perm:[2,3,0,1] row_mask:0xf bank_mask:0xf
	v_add_f32_dpp v60, v60, v60 quad_perm:[2,3,0,1] row_mask:0xf bank_mask:0xf
	v_add_f32_dpp v61, v61, v61 quad_perm:[2,3,0,1] row_mask:0xf bank_mask:0xf
	v_add_f32_dpp v62, v62, v62 quad_perm:[2,3,0,1] row_mask:0xf bank_mask:0xf
	v_add_f32_dpp v63, v63, v63 quad_perm:[2,3,0,1] row_mask:0xf bank_mask:0xf
	v_add_f32_dpp v56, v56, v56 row_half_mirror row_mask:0xf bank_mask:0xf
	v_add_f32_dpp v57, v57, v57 row_half_mirror row_mask:0xf bank_mask:0xf
	v_add_f32_dpp v58, v58, v58 row_half_mirror row_mask:0xf bank_mask:0xf
	v_add_f32_dpp v59, v59, v59 row_half_mirror row_mask:0xf bank_mask:0xf
	v_add_f32_dpp v60, v60, v60 row_half_mirror row_mask:0xf bank_mask:0xf
	v_add_f32_dpp v61, v61, v61 row_half_mirror row_mask:0xf bank_mask:0xf
	v_add_f32_dpp v62, v62, v62 row_half_mirror row_mask:0xf bank_mask:0xf
	v_add_f32_dpp v63, v63, v63 row_half_mirror row_mask:0xf bank_mask:0xf
	v_add_f32_dpp v56, v56, v56 row_mirror row_mask:0xf bank_mask:0xf
	v_add_f32_dpp v57, v57, v57 row_mirror row_mask:0xf bank_mask:0xf
	v_add_f32_dpp v58, v58, v58 row_mirror row_mask:0xf bank_mask:0xf
	v_add_f32_dpp v59, v59, v59 row_mirror row_mask:0xf bank_mask:0xf
	v_add_f32_dpp v60, v60, v60 row_mirror row_mask:0xf bank_mask:0xf
	v_add_f32_dpp v61, v61, v61 row_mirror row_mask:0xf bank_mask:0xf
	v_add_f32_dpp v62, v62, v62 row_mirror row_mask:0xf bank_mask:0xf
	v_add_f32_dpp v63, v63, v63 row_mirror row_mask:0xf bank_mask:0xf
	v_fmamk_f32 v56, v56, 0x3c000000, v225
	v_cmp_gt_f32_e32 vcc, s91, v56
	v_mul_f32_e32 v53, 0x4b800000, v56
	s_nop 0
	v_cndmask_b32_e32 v56, v56, v53, vcc
	v_rsq_f32_e32 v56, v56
	s_nop 0
	v_mul_f32_e32 v53, 0x45800000, v56
	v_cndmask_b32_e32 v56, v56, v53, vcc
	v_mul_f32_e32 v56, v41, v56
	v_fmamk_f32 v57, v57, 0x3c000000, v225
	v_cmp_gt_f32_e32 vcc, s91, v57
	v_mul_f32_e32 v53, 0x4b800000, v57
	s_nop 0
	v_cndmask_b32_e32 v57, v57, v53, vcc
	v_rsq_f32_e32 v57, v57
	s_nop 0
	v_mul_f32_e32 v53, 0x45800000, v57
	v_cndmask_b32_e32 v57, v57, v53, vcc
	v_mul_f32_e32 v57, v41, v57
	v_fmamk_f32 v58, v58, 0x3c000000, v225
	v_cmp_gt_f32_e32 vcc, s91, v58
	v_mul_f32_e32 v53, 0x4b800000, v58
	s_nop 0
	v_cndmask_b32_e32 v58, v58, v53, vcc
	v_rsq_f32_e32 v58, v58
	s_nop 0
	v_mul_f32_e32 v53, 0x45800000, v58
	v_cndmask_b32_e32 v58, v58, v53, vcc
	v_mul_f32_e32 v58, v41, v58
	v_fmamk_f32 v59, v59, 0x3c000000, v225
	v_cmp_gt_f32_e32 vcc, s91, v59
	v_mul_f32_e32 v53, 0x4b800000, v59
	s_nop 0
	v_cndmask_b32_e32 v59, v59, v53, vcc
	v_rsq_f32_e32 v59, v59
	s_nop 0
	v_mul_f32_e32 v53, 0x45800000, v59
	v_cndmask_b32_e32 v59, v59, v53, vcc
	v_mul_f32_e32 v59, v41, v59
	v_fmamk_f32 v60, v60, 0x3c000000, v225
	v_cmp_gt_f32_e32 vcc, s91, v60
	v_mul_f32_e32 v53, 0x4b800000, v60
	s_nop 0
	v_cndmask_b32_e32 v60, v60, v53, vcc
	v_rsq_f32_e32 v60, v60
	s_nop 0
	v_mul_f32_e32 v53, 0x45800000, v60
	v_cndmask_b32_e32 v60, v60, v53, vcc
	v_mul_f32_e32 v60, v41, v60
	v_fmamk_f32 v61, v61, 0x3c000000, v225
	v_cmp_gt_f32_e32 vcc, s91, v61
	v_mul_f32_e32 v53, 0x4b800000, v61
	s_nop 0
	v_cndmask_b32_e32 v61, v61, v53, vcc
	v_rsq_f32_e32 v61, v61
	s_nop 0
	v_mul_f32_e32 v53, 0x45800000, v61
	v_cndmask_b32_e32 v61, v61, v53, vcc
	v_mul_f32_e32 v61, v41, v61
	v_fmamk_f32 v62, v62, 0x3c000000, v225
	v_cmp_gt_f32_e32 vcc, s91, v62
	v_mul_f32_e32 v53, 0x4b800000, v62
	s_nop 0
; __device__ __forceinline__ unsigned pk2(float lo, float hi) { f32x2_t v = {lo, hi}; bf16x2_hw b = __builtin_convertvector(v, bf16x2_hw); return __builtin_bit_cast(unsigned, b); }
; __device__ __forceinline__ void fox_prep(ArgsP a, int j, unsigned char* lds) {
;     ...
;             const float rs = rsqrtf(ss * (1.f / 128.f) + EPS_) * (which == 0 ? 0.12751743f : 1.f);
;             const float* nw = (which == 0 ? qnw : knw) + sub * 8;
;             u32x4 o;
; #pragma unroll
;             for (int e = 0; e < 4; ++e) o[e] = pk2(v[2 * e] * rs * nw[2 * e], v[2 * e + 1] * rs * nw[2 * e + 1]);
;             *(u32x4*)ptr = o; }
	v_cndmask_b32_e32 v62, v62, v53, vcc
	v_rsq_f32_e32 v62, v62
	s_nop 0
	v_mul_f32_e32 v53, 0x45800000, v62
	v_cndmask_b32_e32 v62, v62, v53, vcc
	v_mul_f32_e32 v62, v41, v62
	v_fmamk_f32 v63, v63, 0x3c000000, v225
	v_cmp_gt_f32_e32 vcc, s91, v63
	v_mul_f32_e32 v53, 0x4b800000, v63
	s_nop 0
	v_cndmask_b32_e32 v63, v63, v53, vcc
	v_rsq_f32_e32 v63, v63
	s_nop 0
	v_mul_f32_e32 v53, 0x45800000, v63
	v_cndmask_b32_e32 v63, v63, v53, vcc
	v_mul_f32_e32 v63, v41, v63
	v_add_u32_e32 v31, 0, v36
	v_ashrrev_i32_e32 v34, 3, v31
	v_ashrrev_i32_e32 v35, 31, v34
	v_lshl_add_u64 v[34:35], v[32:33], 0, v[34:35]
	v_lshlrev_b64 v[34:35], 9, v[34:35]
	v_lshl_add_u64 v[34:35], v[8:9], 0, v[34:35]
	v_mov_b32_e32 v74, v56
	v_lshlrev_b32_e32 v72, 16, v188
	v_and_b32_e32 v73, 0xffff0000, v188
	v_pk_mul_f32 v[72:73], v[74:75], v[72:73] op_sel_hi:[0,1]
	s_nop 0
	v_pk_mul_f32 v[72:73], v[220:221], v[72:73]
	s_nop 0
	v_cvt_pk_bf16_f32 v152, v72, v73
	v_lshlrev_b32_e32 v72, 16, v189
	v_and_b32_e32 v73, 0xffff0000, v189
	v_pk_mul_f32 v[72:73], v[74:75], v[72:73] op_sel_hi:[0,1]
	s_nop 0
	v_pk_mul_f32 v[72:73], v[222:223], v[72:73]
	s_nop 0
	v_cvt_pk_bf16_f32 v153, v72, v73
	v_lshlrev_b32_e32 v72, 16, v190
	v_and_b32_e32 v73, 0xffff0000, v190
	v_pk_mul_f32 v[72:73], v[74:75], v[72:73] op_sel_hi:[0,1]
	s_nop 0
	v_pk_mul_f32 v[72:73], v[148:149], v[72:73]
	s_nop 0
	v_cvt_pk_bf16_f32 v154, v72, v73
	v_lshlrev_b32_e32 v72, 16, v191
	v_and_b32_e32 v73, 0xffff0000, v191
	v_pk_mul_f32 v[72:73], v[74:75], v[72:73] op_sel_hi:[0,1]
	s_nop 0
	v_pk_mul_f32 v[72:73], v[150:151], v[72:73]
	s_nop 0
	v_cvt_pk_bf16_f32 v155, v72, v73
	global_store_dwordx4 v[34:35], v[152:155], off
	s_nop 1
	v_add_u32_e32 v31, 32, v36
	v_ashrrev_i32_e32 v34, 3, v31
	v_ashrrev_i32_e32 v35, 31, v34
	v_lshl_add_u64 v[34:35], v[32:33], 0, v[34:35]
	v_lshlrev_b64 v[34:35], 9, v[34:35]
	v_lshl_add_u64 v[34:35], v[8:9], 0, v[34:35]
	v_mov_b32_e32 v74, v57
	v_lshlrev_b32_e32 v72, 16, v192
	v_and_b32_e32 v73, 0xffff0000, v192
	v_pk_mul_f32 v[72:73], v[74:75], v[72:73] op_sel_hi:[0,1]
	s_nop 0
	v_pk_mul_f32 v[72:73], v[220:221], v[72:73]
	s_nop 0
	v_cvt_pk_bf16_f32 v152, v72, v73
	v_lshlrev_b32_e32 v72, 16, v193
	v_and_b32_e32 v73, 0xffff0000, v193
	v_pk_mul_f32 v[72:73], v[74:75], v[72:73] op_sel_hi:[0,1]
	s_nop 0
	v_pk_mul_f32 v[72:73], v[222:223], v[72:73]
	s_nop 0
	v_cvt_pk_bf16_f32 v153, v72, v73
	v_lshlrev_b32_e32 v72, 16, v194
	v_and_b32_e32 v73, 0xffff0000, v194
	v_pk_mul_f32 v[72:73], v[74:75], v[72:73] op_sel_hi:[0,1]
	s_nop 0
	v_pk_mul_f32 v[72:73], v[148:149], v[72:73]
	s_nop 0
	v_cvt_pk_bf16_f32 v154, v72, v73
	v_lshlrev_b32_e32 v72, 16, v195
	v_and_b32_e32 v73, 0xffff0000, v195
	v_pk_mul_f32 v[72:73], v[74:75], v[72:73] op_sel_hi:[0,1]
	s_nop 0
	v_pk_mul_f32 v[72:73], v[150:151], v[72:73]
	s_nop 0
	v_cvt_pk_bf16_f32 v155, v72, v73
	global_store_dwordx4 v[34:35], v[152:155], off
	s_nop 1
	v_add_u32_e32 v31, 64, v36
	v_ashrrev_i32_e32 v34, 3, v31
	v_ashrrev_i32_e32 v35, 31, v34
	v_lshl_add_u64 v[34:35], v[32:33], 0, v[34:35]
	v_lshlrev_b64 v[34:35], 9, v[34:35]
	v_lshl_add_u64 v[34:35], v[8:9], 0, v[34:35]
	v_mov_b32_e32 v74, v58
	v_lshlrev_b32_e32 v72, 16, v196
	v_and_b32_e32 v73, 0xffff0000, v196
	v_pk_mul_f32 v[72:73], v[74:75], v[72:73] op_sel_hi:[0,1]
	s_nop 0
	v_pk_mul_f32 v[72:73], v[220:221], v[72:73]
	s_nop 0
	v_cvt_pk_bf16_f32 v152, v72, v73
	v_lshlrev_b32_e32 v72, 16, v197
	v_and_b32_e32 v73, 0xffff0000, v197
	v_pk_mul_f32 v[72:73], v[74:75], v[72:73] op_sel_hi:[0,1]
	s_nop 0
	v_pk_mul_f32 v[72:73], v[222:223], v[72:73]
	s_nop 0
	v_cvt_pk_bf16_f32 v153, v72, v73
	v_lshlrev_b32_e32 v72, 16, v198
	v_and_b32_e32 v73, 0xffff0000, v198
	v_pk_mul_f32 v[72:73], v[74:75], v[72:73] op_sel_hi:[0,1]
	s_nop 0
	v_pk_mul_f32 v[72:73], v[148:149], v[72:73]
	s_nop 0
	v_cvt_pk_bf16_f32 v154, v72, v73
	v_lshlrev_b32_e32 v72, 16, v199
	v_and_b32_e32 v73, 0xffff0000, v199
	v_pk_mul_f32 v[72:73], v[74:75], v[72:73] op_sel_hi:[0,1]
	s_nop 0
	v_pk_mul_f32 v[72:73], v[150:151], v[72:73]
	s_nop 0
	v_cvt_pk_bf16_f32 v155, v72, v73
	global_store_dwordx4 v[34:35], v[152:155], off
	s_nop 1
	v_add_u32_e32 v31, 0x60, v36
	v_ashrrev_i32_e32 v34, 3, v31
	v_ashrrev_i32_e32 v35, 31, v34
	v_lshl_add_u64 v[34:35], v[32:33], 0, v[34:35]
	v_lshlrev_b64 v[34:35], 9, v[34:35]
	v_lshl_add_u64 v[34:35], v[8:9], 0, v[34:35]
	v_mov_b32_e32 v74, v59
	v_lshlrev_b32_e32 v72, 16, v200
	v_and_b32_e32 v73, 0xffff0000, v200
	v_pk_mul_f32 v[72:73], v[74:75], v[72:73] op_sel_hi:[0,1]
	s_nop 0
	v_pk_mul_f32 v[72:73], v[220:221], v[72:73]
	s_nop 0
	v_cvt_pk_bf16_f32 v152, v72, v73
	v_lshlrev_b32_e32 v72, 16, v201
	v_and_b32_e32 v73, 0xffff0000, v201
	v_pk_mul_f32 v[72:73], v[74:75], v[72:73] op_sel_hi:[0,1]
	s_nop 0
	v_pk_mul_f32 v[72:73], v[222:223], v[72:73]
	s_nop 0
	v_cvt_pk_bf16_f32 v153, v72, v73
	v_lshlrev_b32_e32 v72, 16, v202
	v_and_b32_e32 v73, 0xffff0000, v202
	v_pk_mul_f32 v[72:73], v[74:75], v[72:73] op_sel_hi:[0,1]
	s_nop 0
	v_pk_mul_f32 v[72:73], v[148:149], v[72:73]
	s_nop 0
	v_cvt_pk_bf16_f32 v154, v72, v73
	v_lshlrev_b32_e32 v72, 16, v203
	v_and_b32_e32 v73, 0xffff0000, v203
	v_pk_mul_f32 v[72:73], v[74:75], v[72:73] op_sel_hi:[0,1]
	s_nop 0
	v_pk_mul_f32 v[72:73], v[150:151], v[72:73]
	s_nop 0
	v_cvt_pk_bf16_f32 v155, v72, v73
	global_store_dwordx4 v[34:35], v[152:155], off
	s_nop 1
	v_add_u32_e32 v31, 0x80, v36
	v_ashrrev_i32_e32 v34, 3, v31
	v_ashrrev_i32_e32 v35, 31, v34
	v_lshl_add_u64 v[34:35], v[32:33], 0, v[34:35]
	v_lshlrev_b64 v[34:35], 9, v[34:35]
	v_lshl_add_u64 v[34:35], v[8:9], 0, v[34:35]
	v_mov_b32_e32 v74, v60
	v_lshlrev_b32_e32 v72, 16, v204
	v_and_b32_e32 v73, 0xffff0000, v204
; __device__ __forceinline__ unsigned pk2(float lo, float hi) { f32x2_t v = {lo, hi}; bf16x2_hw b = __builtin_convertvector(v, bf16x2_hw); return __builtin_bit_cast(unsigned, b); }
; __device__ __forceinline__ void fox_prep(ArgsP a, int j, unsigned char* lds) {
;     ...
;             const float rs = rsqrtf(ss * (1.f / 128.f) + EPS_) * (which == 0 ? 0.12751743f : 1.f);
;             const float* nw = (which == 0 ? qnw : knw) + sub * 8;
;             u32x4 o;
; #pragma unroll
;             for (int e = 0; e < 4; ++e) o[e] = pk2(v[2 * e] * rs * nw[2 * e], v[2 * e + 1] * rs * nw[2 * e + 1]);
;             *(u32x4*)ptr = o; }
	v_pk_mul_f32 v[72:73], v[74:75], v[72:73] op_sel_hi:[0,1]
	s_nop 0
	v_pk_mul_f32 v[72:73], v[220:221], v[72:73]
	s_nop 0
	v_cvt_pk_bf16_f32 v152, v72, v73
	v_lshlrev_b32_e32 v72, 16, v205
	v_and_b32_e32 v73, 0xffff0000, v205
	v_pk_mul_f32 v[72:73], v[74:75], v[72:73] op_sel_hi:[0,1]
	s_nop 0
	v_pk_mul_f32 v[72:73], v[222:223], v[72:73]
	s_nop 0
	v_cvt_pk_bf16_f32 v153, v72, v73
	v_lshlrev_b32_e32 v72, 16, v206
	v_and_b32_e32 v73, 0xffff0000, v206
	v_pk_mul_f32 v[72:73], v[74:75], v[72:73] op_sel_hi:[0,1]
	s_nop 0
	v_pk_mul_f32 v[72:73], v[148:149], v[72:73]
	s_nop 0
	v_cvt_pk_bf16_f32 v154, v72, v73
	v_lshlrev_b32_e32 v72, 16, v207
	v_and_b32_e32 v73, 0xffff0000, v207
	v_pk_mul_f32 v[72:73], v[74:75], v[72:73] op_sel_hi:[0,1]
	s_nop 0
	v_pk_mul_f32 v[72:73], v[150:151], v[72:73]
	s_nop 0
	v_cvt_pk_bf16_f32 v155, v72, v73
	global_store_dwordx4 v[34:35], v[152:155], off
	s_nop 1
	v_add_u32_e32 v31, 0xa0, v36
	v_ashrrev_i32_e32 v34, 3, v31
	v_ashrrev_i32_e32 v35, 31, v34
	v_lshl_add_u64 v[34:35], v[32:33], 0, v[34:35]
	v_lshlrev_b64 v[34:35], 9, v[34:35]
	v_lshl_add_u64 v[34:35], v[8:9], 0, v[34:35]
	v_mov_b32_e32 v74, v61
	v_lshlrev_b32_e32 v72, 16, v208
	v_and_b32_e32 v73, 0xffff0000, v208
	v_pk_mul_f32 v[72:73], v[74:75], v[72:73] op_sel_hi:[0,1]
	s_nop 0
	v_pk_mul_f32 v[72:73], v[220:221], v[72:73]
	s_nop 0
	v_cvt_pk_bf16_f32 v152, v72, v73
	v_lshlrev_b32_e32 v72, 16, v209
	v_and_b32_e32 v73, 0xffff0000, v209
	v_pk_mul_f32 v[72:73], v[74:75], v[72:73] op_sel_hi:[0,1]
	s_nop 0
	v_pk_mul_f32 v[72:73], v[222:223], v[72:73]
	s_nop 0
	v_cvt_pk_bf16_f32 v153, v72, v73
	v_lshlrev_b32_e32 v72, 16, v210
	v_and_b32_e32 v73, 0xffff0000, v210
	v_pk_mul_f32 v[72:73], v[74:75], v[72:73] op_sel_hi:[0,1]
	s_nop 0
	v_pk_mul_f32 v[72:73], v[148:149], v[72:73]
	s_nop 0
	v_cvt_pk_bf16_f32 v154, v72, v73
	v_lshlrev_b32_e32 v72, 16, v211
	v_and_b32_e32 v73, 0xffff0000, v211
	v_pk_mul_f32 v[72:73], v[74:75], v[72:73] op_sel_hi:[0,1]
	s_nop 0
	v_pk_mul_f32 v[72:73], v[150:151], v[72:73]
	s_nop 0
	v_cvt_pk_bf16_f32 v155, v72, v73
	global_store_dwordx4 v[34:35], v[152:155], off
	s_nop 1
	v_add_u32_e32 v31, 0xc0, v36
	v_ashrrev_i32_e32 v34, 3, v31
	v_ashrrev_i32_e32 v35, 31, v34
	v_lshl_add_u64 v[34:35], v[32:33], 0, v[34:35]
	v_lshlrev_b64 v[34:35], 9, v[34:35]
	v_lshl_add_u64 v[34:35], v[8:9], 0, v[34:35]
	v_mov_b32_e32 v74, v62
	v_lshlrev_b32_e32 v72, 16, v212
	v_and_b32_e32 v73, 0xffff0000, v212
	v_pk_mul_f32 v[72:73], v[74:75], v[72:73] op_sel_hi:[0,1]
	s_nop 0
	v_pk_mul_f32 v[72:73], v[220:221], v[72:73]
	s_nop 0
	v_cvt_pk_bf16_f32 v152, v72, v73
	v_lshlrev_b32_e32 v72, 16, v213
	v_and_b32_e32 v73, 0xffff0000, v213
	v_pk_mul_f32 v[72:73], v[74:75], v[72:73] op_sel_hi:[0,1]
	s_nop 0
	v_pk_mul_f32 v[72:73], v[222:223], v[72:73]
	s_nop 0
	v_cvt_pk_bf16_f32 v153, v72, v73
	v_lshlrev_b32_e32 v72, 16, v214
	v_and_b32_e32 v73, 0xffff0000, v214
	v_pk_mul_f32 v[72:73], v[74:75], v[72:73] op_sel_hi:[0,1]
	s_nop 0
	v_pk_mul_f32 v[72:73], v[148:149], v[72:73]
	s_nop 0
	v_cvt_pk_bf16_f32 v154, v72, v73
	v_lshlrev_b32_e32 v72, 16, v215
	v_and_b32_e32 v73, 0xffff0000, v215
	v_pk_mul_f32 v[72:73], v[74:75], v[72:73] op_sel_hi:[0,1]
	s_nop 0
	v_pk_mul_f32 v[72:73], v[150:151], v[72:73]
	s_nop 0
	v_cvt_pk_bf16_f32 v155, v72, v73
	global_store_dwordx4 v[34:35], v[152:155], off
	s_nop 1
	v_add_u32_e32 v31, 0xe0, v36
	v_ashrrev_i32_e32 v34, 3, v31
	v_ashrrev_i32_e32 v35, 31, v34
	v_lshl_add_u64 v[34:35], v[32:33], 0, v[34:35]
	v_lshlrev_b64 v[34:35], 9, v[34:35]
	v_lshl_add_u64 v[34:35], v[8:9], 0, v[34:35]
	v_mov_b32_e32 v74, v63
	v_lshlrev_b32_e32 v72, 16, v216
	v_and_b32_e32 v73, 0xffff0000, v216
	v_pk_mul_f32 v[72:73], v[74:75], v[72:73] op_sel_hi:[0,1]
	s_nop 0
	v_pk_mul_f32 v[72:73], v[220:221], v[72:73]
	s_nop 0
	v_cvt_pk_bf16_f32 v152, v72, v73
	v_lshlrev_b32_e32 v72, 16, v217
	v_and_b32_e32 v73, 0xffff0000, v217
	v_pk_mul_f32 v[72:73], v[74:75], v[72:73] op_sel_hi:[0,1]
	s_nop 0
	v_pk_mul_f32 v[72:73], v[222:223], v[72:73]
	s_nop 0
	v_cvt_pk_bf16_f32 v153, v72, v73
	v_lshlrev_b32_e32 v72, 16, v218
	v_and_b32_e32 v73, 0xffff0000, v218
	v_pk_mul_f32 v[72:73], v[74:75], v[72:73] op_sel_hi:[0,1]
	s_nop 0
	v_pk_mul_f32 v[72:73], v[148:149], v[72:73]
	s_nop 0
	v_cvt_pk_bf16_f32 v154, v72, v73
	v_lshlrev_b32_e32 v72, 16, v219
	v_and_b32_e32 v73, 0xffff0000, v219
	v_pk_mul_f32 v[72:73], v[74:75], v[72:73] op_sel_hi:[0,1]
	s_nop 0
	v_pk_mul_f32 v[72:73], v[150:151], v[72:73]
	s_nop 0
	v_cvt_pk_bf16_f32 v155, v72, v73
	global_store_dwordx4 v[34:35], v[152:155], off
	s_nop 1
	s_waitcnt vmcnt(0)
; __device__ __forceinline__ float bflo(unsigned u) { return __uint_as_float(u << 16); }
; __device__ __forceinline__ float bfhi(unsigned u) { return __uint_as_float(u & 0xffff0000u); }
; __device__ __forceinline__ void fox_prep(ArgsP a, int j, unsigned char* lds) {
;     ...
;         for (int p = 0; p < 16; ++p) { const int grp = p * 32 + (tid >> 4), sub = tid & 15; const int r = grp >> 3, which = (grp >> 2) & 1, h = grp & 3;
;             bf16* ptr = BIG + BIGX(r0 + r, 2048 + which * 512 + h * 128 + sub * 8);
;             const u32x4 w = *(const u32x4*)ptr; float v[8];
; #pragma unroll
;             for (int e = 0; e < 4; ++e) { v[2 * e] = bflo(w[e]); v[2 * e + 1] = bfhi(w[e]); }
;             float ss = 0.f;
; #pragma unroll
;             for (int e = 0; e < 8; ++e) ss += v[e] * v[e];
	v_lshlrev_b32_e32 v72, 16, v112
	v_and_b32_e32 v73, 0xffff0000, v112
	v_pk_mul_f32 v[74:75], v[72:73], v[72:73]
	s_nop 0
	v_add_f32_e32 v64, v74, v75
	v_lshlrev_b32_e32 v72, 16, v113
	v_and_b32_e32 v73, 0xffff0000, v113
	v_pk_mul_f32 v[74:75], v[72:73], v[72:73]
	s_nop 0
	v_add_f32_e32 v64, v74, v64
	v_add_f32_e32 v64, v75, v64
	v_lshlrev_b32_e32 v72, 16, v114
	v_and_b32_e32 v73, 0xffff0000, v114
	v_pk_mul_f32 v[74:75], v[72:73], v[72:73]
	s_nop 0
	v_add_f32_e32 v64, v74, v64
	v_add_f32_e32 v64, v75, v64
	v_lshlrev_b32_e32 v72, 16, v115
	v_and_b32_e32 v73, 0xffff0000, v115
	v_pk_mul_f32 v[74:75], v[72:73], v[72:73]
	s_nop 0
	v_add_f32_e32 v64, v74, v64
	v_add_f32_e32 v64, v75, v64
	v_lshlrev_b32_e32 v72, 16, v116
	v_and_b32_e32 v73, 0xffff0000, v116
	v_pk_mul_f32 v[74:75], v[72:73], v[72:73]
	s_nop 0
	v_add_f32_e32 v65, v74, v75
	v_lshlrev_b32_e32 v72, 16, v117
	v_and_b32_e32 v73, 0xffff0000, v117
	v_pk_mul_f32 v[74:75], v[72:73], v[72:73]
	s_nop 0
	v_add_f32_e32 v65, v74, v65
	v_add_f32_e32 v65, v75, v65
	v_lshlrev_b32_e32 v72, 16, v118
	v_and_b32_e32 v73, 0xffff0000, v118
	v_pk_mul_f32 v[74:75], v[72:73], v[72:73]
	s_nop 0
	v_add_f32_e32 v65, v74, v65
	v_add_f32_e32 v65, v75, v65
	v_lshlrev_b32_e32 v72, 16, v119
	v_and_b32_e32 v73, 0xffff0000, v119
	v_pk_mul_f32 v[74:75], v[72:73], v[72:73]
	s_nop 0
	v_add_f32_e32 v65, v74, v65
	v_add_f32_e32 v65, v75, v65
	v_lshlrev_b32_e32 v72, 16, v120
	v_and_b32_e32 v73, 0xffff0000, v120
	v_pk_mul_f32 v[74:75], v[72:73], v[72:73]
	s_nop 0
	v_add_f32_e32 v66, v74, v75
	v_lshlrev_b32_e32 v72, 16, v121
	v_and_b32_e32 v73, 0xffff0000, v121
	v_pk_mul_f32 v[74:75], v[72:73], v[72:73]
	s_nop 0
	v_add_f32_e32 v66, v74, v66
	v_add_f32_e32 v66, v75, v66
	v_lshlrev_b32_e32 v72, 16, v122
	v_and_b32_e32 v73, 0xffff0000, v122
	v_pk_mul_f32 v[74:75], v[72:73], v[72:73]
	s_nop 0
	v_add_f32_e32 v66, v74, v66
	v_add_f32_e32 v66, v75, v66
	v_lshlrev_b32_e32 v72, 16, v123
	v_and_b32_e32 v73, 0xffff0000, v123
	v_pk_mul_f32 v[74:75], v[72:73], v[72:73]
	s_nop 0
	v_add_f32_e32 v66, v74, v66
	v_add_f32_e32 v66, v75, v66
	v_lshlrev_b32_e32 v72, 16, v124
	v_and_b32_e32 v73, 0xffff0000, v124
	v_pk_mul_f32 v[74:75], v[72:73], v[72:73]
	s_nop 0
	v_add_f32_e32 v67, v74, v75
	v_lshlrev_b32_e32 v72, 16, v125
	v_and_b32_e32 v73, 0xffff0000, v125
	v_pk_mul_f32 v[74:75], v[72:73], v[72:73]
	s_nop 0
	v_add_f32_e32 v67, v74, v67
	v_add_f32_e32 v67, v75, v67
	v_lshlrev_b32_e32 v72, 16, v126
	v_and_b32_e32 v73, 0xffff0000, v126
	v_pk_mul_f32 v[74:75], v[72:73], v[72:73]
	s_nop 0
	v_add_f32_e32 v67, v74, v67
	v_add_f32_e32 v67, v75, v67
	v_lshlrev_b32_e32 v72, 16, v127
	v_and_b32_e32 v73, 0xffff0000, v127
	v_pk_mul_f32 v[74:75], v[72:73], v[72:73]
	s_nop 0
	v_add_f32_e32 v67, v74, v67
	v_add_f32_e32 v67, v75, v67
	v_lshlrev_b32_e32 v72, 16, v128
	v_and_b32_e32 v73, 0xffff0000, v128
	v_pk_mul_f32 v[74:75], v[72:73], v[72:73]
	s_nop 0
	v_add_f32_e32 v68, v74, v75
	v_lshlrev_b32_e32 v72, 16, v129
	v_and_b32_e32 v73, 0xffff0000, v129
	v_pk_mul_f32 v[74:75], v[72:73], v[72:73]
	s_nop 0
	v_add_f32_e32 v68, v74, v68
	v_add_f32_e32 v68, v75, v68
	v_lshlrev_b32_e32 v72, 16, v130
	v_and_b32_e32 v73, 0xffff0000, v130
	v_pk_mul_f32 v[74:75], v[72:73], v[72:73]
	s_nop 0
	v_add_f32_e32 v68, v74, v68
	v_add_f32_e32 v68, v75, v68
	v_lshlrev_b32_e32 v72, 16, v131
	v_and_b32_e32 v73, 0xffff0000, v131
	v_pk_mul_f32 v[74:75], v[72:73], v[72:73]
	s_nop 0
	v_add_f32_e32 v68, v74, v68
	v_add_f32_e32 v68, v75, v68
	v_lshlrev_b32_e32 v72, 16, v132
	v_and_b32_e32 v73, 0xffff0000, v132
	v_pk_mul_f32 v[74:75], v[72:73], v[72:73]
	s_nop 0
	v_add_f32_e32 v69, v74, v75
	v_lshlrev_b32_e32 v72, 16, v133
	v_and_b32_e32 v73, 0xffff0000, v133
	v_pk_mul_f32 v[74:75], v[72:73], v[72:73]
	s_nop 0
	v_add_f32_e32 v69, v74, v69
	v_add_f32_e32 v69, v75, v69
	v_lshlrev_b32_e32 v72, 16, v134
	v_and_b32_e32 v73, 0xffff0000, v134
	v_pk_mul_f32 v[74:75], v[72:73], v[72:73]
	s_nop 0
	v_add_f32_e32 v69, v74, v69
	v_add_f32_e32 v69, v75, v69
	v_lshlrev_b32_e32 v72, 16, v135
	v_and_b32_e32 v73, 0xffff0000, v135
	v_pk_mul_f32 v[74:75], v[72:73], v[72:73]
	s_nop 0
	v_add_f32_e32 v69, v74, v69
	v_add_f32_e32 v69, v75, v69
	v_lshlrev_b32_e32 v72, 16, v136
	v_and_b32_e32 v73, 0xffff0000, v136
	v_pk_mul_f32 v[74:75], v[72:73], v[72:73]
	s_nop 0
	v_add_f32_e32 v70, v74, v75
	v_lshlrev_b32_e32 v72, 16, v137
	v_and_b32_e32 v73, 0xffff0000, v137
	v_pk_mul_f32 v[74:75], v[72:73], v[72:73]
	s_nop 0
	v_add_f32_e32 v70, v74, v70
	v_add_f32_e32 v70, v75, v70
	v_lshlrev_b32_e32 v72, 16, v138
	v_and_b32_e32 v73, 0xffff0000, v138
	v_pk_mul_f32 v[74:75], v[72:73], v[72:73]
	s_nop 0
	v_add_f32_e32 v70, v74, v70
	v_add_f32_e32 v70, v75, v70
	v_lshlrev_b32_e32 v72, 16, v139
	v_and_b32_e32 v73, 0xffff0000, v139
	v_pk_mul_f32 v[74:75], v[72:73], v[72:73]
	s_nop 0
	v_add_f32_e32 v70, v74, v70
	v_add_f32_e32 v70, v75, v70
	v_lshlrev_b32_e32 v72, 16, v140
	v_and_b32_e32 v73, 0xffff0000, v140
	v_pk_mul_f32 v[74:75], v[72:73], v[72:73]
	s_nop 0
	v_add_f32_e32 v71, v74, v75
	v_lshlrev_b32_e32 v72, 16, v141
	v_and_b32_e32 v73, 0xffff0000, v141
	v_pk_mul_f32 v[74:75], v[72:73], v[72:73]
	s_nop 0
	v_add_f32_e32 v71, v74, v71
	v_add_f32_e32 v71, v75, v71
	v_lshlrev_b32_e32 v72, 16, v142
	v_and_b32_e32 v73, 0xffff0000, v142
	v_pk_mul_f32 v[74:75], v[72:73], v[72:73]
	s_nop 0
	v_add_f32_e32 v71, v74, v71
	v_add_f32_e32 v71, v75, v71
	v_lshlrev_b32_e32 v72, 16, v143
	v_and_b32_e32 v73, 0xffff0000, v143
	v_pk_mul_f32 v[74:75], v[72:73], v[72:73]
	s_nop 0
	v_add_f32_e32 v71, v74, v71
	v_add_f32_e32 v71, v75, v71
	v_add_f32_dpp v64, v64, v64 quad_perm:[1,0,3,2] row_mask:0xf bank_mask:0xf
; __device__ __forceinline__ unsigned pk2(float lo, float hi) { f32x2_t v = {lo, hi}; bf16x2_hw b = __builtin_convertvector(v, bf16x2_hw); return __builtin_bit_cast(unsigned, b); }
; __device__ __forceinline__ void fox_prep(ArgsP a, int j, unsigned char* lds) {
;     ...
;             float ss = 0.f;
; #pragma unroll
;             for (int e = 0; e < 8; ++e) ss += v[e] * v[e];
;             ss += __shfl_xor(ss, 1); ss += __shfl_xor(ss, 2); ss += __shfl_xor(ss, 4); ss += __shfl_xor(ss, 8);
;             const float rs = rsqrtf(ss * (1.f / 128.f) + EPS_) * (which == 0 ? 0.12751743f : 1.f);
;             const float* nw = (which == 0 ? qnw : knw) + sub * 8;
;             u32x4 o;
; #pragma unroll
;             for (int e = 0; e < 4; ++e) o[e] = pk2(v[2 * e] * rs * nw[2 * e], v[2 * e + 1] * rs * nw[2 * e + 1]);
;             *(u32x4*)ptr = o; }
	v_add_f32_dpp v65, v65, v65 quad_perm:[1,0,3,2] row_mask:0xf bank_mask:0xf
	v_add_f32_dpp v66, v66, v66 quad_perm:[1,0,3,2] row_mask:0xf bank_mask:0xf
	v_add_f32_dpp v67, v67, v67 quad_perm:[1,0,3,2] row_mask:0xf bank_mask:0xf
	v_add_f32_dpp v68, v68, v68 quad_perm:[1,0,3,2] row_mask:0xf bank_mask:0xf
	v_add_f32_dpp v69, v69, v69 quad_perm:[1,0,3,2] row_mask:0xf bank_mask:0xf
	v_add_f32_dpp v70, v70, v70 quad_perm:[1,0,3,2] row_mask:0xf bank_mask:0xf
	v_add_f32_dpp v71, v71, v71 quad_perm:[1,0,3,2] row_mask:0xf bank_mask:0xf
	v_add_f32_dpp v64, v64, v64 quad_perm:[2,3,0,1] row_mask:0xf bank_mask:0xf
	v_add_f32_dpp v65, v65, v65 quad_perm:[2,3,0,1] row_mask:0xf bank_mask:0xf
	v_add_f32_dpp v66, v66, v66 quad_perm:[2,3,0,1] row_mask:0xf bank_mask:0xf
	v_add_f32_dpp v67, v67, v67 quad_perm:[2,3,0,1] row_mask:0xf bank_mask:0xf
	v_add_f32_dpp v68, v68, v68 quad_perm:[2,3,0,1] row_mask:0xf bank_mask:0xf
	v_add_f32_dpp v69, v69, v69 quad_perm:[2,3,0,1] row_mask:0xf bank_mask:0xf
	v_add_f32_dpp v70, v70, v70 quad_perm:[2,3,0,1] row_mask:0xf bank_mask:0xf
	v_add_f32_dpp v71, v71, v71 quad_perm:[2,3,0,1] row_mask:0xf bank_mask:0xf
	v_add_f32_dpp v64, v64, v64 row_half_mirror row_mask:0xf bank_mask:0xf
	v_add_f32_dpp v65, v65, v65 row_half_mirror row_mask:0xf bank_mask:0xf
	v_add_f32_dpp v66, v66, v66 row_half_mirror row_mask:0xf bank_mask:0xf
	v_add_f32_dpp v67, v67, v67 row_half_mirror row_mask:0xf bank_mask:0xf
	v_add_f32_dpp v68, v68, v68 row_half_mirror row_mask:0xf bank_mask:0xf
	v_add_f32_dpp v69, v69, v69 row_half_mirror row_mask:0xf bank_mask:0xf
	v_add_f32_dpp v70, v70, v70 row_half_mirror row_mask:0xf bank_mask:0xf
	v_add_f32_dpp v71, v71, v71 row_half_mirror row_mask:0xf bank_mask:0xf
	v_add_f32_dpp v64, v64, v64 row_mirror row_mask:0xf bank_mask:0xf
	v_add_f32_dpp v65, v65, v65 row_mirror row_mask:0xf bank_mask:0xf
	v_add_f32_dpp v66, v66, v66 row_mirror row_mask:0xf bank_mask:0xf
	v_add_f32_dpp v67, v67, v67 row_mirror row_mask:0xf bank_mask:0xf
	v_add_f32_dpp v68, v68, v68 row_mirror row_mask:0xf bank_mask:0xf
	v_add_f32_dpp v69, v69, v69 row_mirror row_mask:0xf bank_mask:0xf
	v_add_f32_dpp v70, v70, v70 row_mirror row_mask:0xf bank_mask:0xf
	v_add_f32_dpp v71, v71, v71 row_mirror row_mask:0xf bank_mask:0xf
	v_fmamk_f32 v64, v64, 0x3c000000, v225
	v_cmp_gt_f32_e32 vcc, s91, v64
	v_mul_f32_e32 v53, 0x4b800000, v64
	s_nop 0
	v_cndmask_b32_e32 v64, v64, v53, vcc
	v_rsq_f32_e32 v64, v64
	s_nop 0
	v_mul_f32_e32 v53, 0x45800000, v64
	v_cndmask_b32_e32 v64, v64, v53, vcc
	v_mul_f32_e32 v64, v41, v64
	v_fmamk_f32 v65, v65, 0x3c000000, v225
	v_cmp_gt_f32_e32 vcc, s91, v65
	v_mul_f32_e32 v53, 0x4b800000, v65
	s_nop 0
	v_cndmask_b32_e32 v65, v65, v53, vcc
	v_rsq_f32_e32 v65, v65
	s_nop 0
	v_mul_f32_e32 v53, 0x45800000, v65
	v_cndmask_b32_e32 v65, v65, v53, vcc
	v_mul_f32_e32 v65, v41, v65
	v_fmamk_f32 v66, v66, 0x3c000000, v225
	v_cmp_gt_f32_e32 vcc, s91, v66
	v_mul_f32_e32 v53, 0x4b800000, v66
	s_nop 0
	v_cndmask_b32_e32 v66, v66, v53, vcc
	v_rsq_f32_e32 v66, v66
	s_nop 0
	v_mul_f32_e32 v53, 0x45800000, v66
	v_cndmask_b32_e32 v66, v66, v53, vcc
	v_mul_f32_e32 v66, v41, v66
	v_fmamk_f32 v67, v67, 0x3c000000, v225
	v_cmp_gt_f32_e32 vcc, s91, v67
	v_mul_f32_e32 v53, 0x4b800000, v67
	s_nop 0
	v_cndmask_b32_e32 v67, v67, v53, vcc
	v_rsq_f32_e32 v67, v67
	s_nop 0
	v_mul_f32_e32 v53, 0x45800000, v67
	v_cndmask_b32_e32 v67, v67, v53, vcc
	v_mul_f32_e32 v67, v41, v67
	v_fmamk_f32 v68, v68, 0x3c000000, v225
	v_cmp_gt_f32_e32 vcc, s91, v68
	v_mul_f32_e32 v53, 0x4b800000, v68
	s_nop 0
	v_cndmask_b32_e32 v68, v68, v53, vcc
	v_rsq_f32_e32 v68, v68
	s_nop 0
	v_mul_f32_e32 v53, 0x45800000, v68
	v_cndmask_b32_e32 v68, v68, v53, vcc
	v_mul_f32_e32 v68, v41, v68
	v_fmamk_f32 v69, v69, 0x3c000000, v225
	v_cmp_gt_f32_e32 vcc, s91, v69
	v_mul_f32_e32 v53, 0x4b800000, v69
	s_nop 0
	v_cndmask_b32_e32 v69, v69, v53, vcc
	v_rsq_f32_e32 v69, v69
	s_nop 0
	v_mul_f32_e32 v53, 0x45800000, v69
	v_cndmask_b32_e32 v69, v69, v53, vcc
	v_mul_f32_e32 v69, v41, v69
	v_fmamk_f32 v70, v70, 0x3c000000, v225
	v_cmp_gt_f32_e32 vcc, s91, v70
	v_mul_f32_e32 v53, 0x4b800000, v70
	s_nop 0
	v_cndmask_b32_e32 v70, v70, v53, vcc
	v_rsq_f32_e32 v70, v70
	s_nop 0
	v_mul_f32_e32 v53, 0x45800000, v70
	v_cndmask_b32_e32 v70, v70, v53, vcc
	v_mul_f32_e32 v70, v41, v70
	v_fmamk_f32 v71, v71, 0x3c000000, v225
	v_cmp_gt_f32_e32 vcc, s91, v71
	v_mul_f32_e32 v53, 0x4b800000, v71
	s_nop 0
	v_cndmask_b32_e32 v71, v71, v53, vcc
	v_rsq_f32_e32 v71, v71
	s_nop 0
	v_mul_f32_e32 v53, 0x45800000, v71
	v_cndmask_b32_e32 v71, v71, v53, vcc
	v_mul_f32_e32 v71, v41, v71
	v_add_u32_e32 v31, 0x100, v36
	v_ashrrev_i32_e32 v34, 3, v31
	v_ashrrev_i32_e32 v35, 31, v34
	v_lshl_add_u64 v[34:35], v[32:33], 0, v[34:35]
	v_lshlrev_b64 v[34:35], 9, v[34:35]
	v_lshl_add_u64 v[34:35], v[8:9], 0, v[34:35]
	v_mov_b32_e32 v74, v64
	v_lshlrev_b32_e32 v72, 16, v112
	v_and_b32_e32 v73, 0xffff0000, v112
	v_pk_mul_f32 v[72:73], v[74:75], v[72:73] op_sel_hi:[0,1]
	s_nop 0
	v_pk_mul_f32 v[72:73], v[220:221], v[72:73]
	s_nop 0
	v_cvt_pk_bf16_f32 v152, v72, v73
	v_lshlrev_b32_e32 v72, 16, v113
	v_and_b32_e32 v73, 0xffff0000, v113
	v_pk_mul_f32 v[72:73], v[74:75], v[72:73] op_sel_hi:[0,1]
	s_nop 0
	v_pk_mul_f32 v[72:73], v[222:223], v[72:73]
	s_nop 0
	v_cvt_pk_bf16_f32 v153, v72, v73
	v_lshlrev_b32_e32 v72, 16, v114
	v_and_b32_e32 v73, 0xffff0000, v114
	v_pk_mul_f32 v[72:73], v[74:75], v[72:73] op_sel_hi:[0,1]
	s_nop 0
	v_pk_mul_f32 v[72:73], v[148:149], v[72:73]
	s_nop 0
	v_cvt_pk_bf16_f32 v154, v72, v73
	v_lshlrev_b32_e32 v72, 16, v115
	v_and_b32_e32 v73, 0xffff0000, v115
	v_pk_mul_f32 v[72:73], v[74:75], v[72:73] op_sel_hi:[0,1]
; __device__ __forceinline__ unsigned pk2(float lo, float hi) { f32x2_t v = {lo, hi}; bf16x2_hw b = __builtin_convertvector(v, bf16x2_hw); return __builtin_bit_cast(unsigned, b); }
; __device__ __forceinline__ void fox_prep(ArgsP a, int j, unsigned char* lds) {
;     ...
;             const float rs = rsqrtf(ss * (1.f / 128.f) + EPS_) * (which == 0 ? 0.12751743f : 1.f);
;             const float* nw = (which == 0 ? qnw : knw) + sub * 8;
;             u32x4 o;
; #pragma unroll
;             for (int e = 0; e < 4; ++e) o[e] = pk2(v[2 * e] * rs * nw[2 * e], v[2 * e + 1] * rs * nw[2 * e + 1]);
;             *(u32x4*)ptr = o; }
	s_nop 0
	v_pk_mul_f32 v[72:73], v[150:151], v[72:73]
	s_nop 0
	v_cvt_pk_bf16_f32 v155, v72, v73
	global_store_dwordx4 v[34:35], v[152:155], off
	s_nop 1
	v_add_u32_e32 v31, 0x120, v36
	v_ashrrev_i32_e32 v34, 3, v31
	v_ashrrev_i32_e32 v35, 31, v34
	v_lshl_add_u64 v[34:35], v[32:33], 0, v[34:35]
	v_lshlrev_b64 v[34:35], 9, v[34:35]
	v_lshl_add_u64 v[34:35], v[8:9], 0, v[34:35]
	v_mov_b32_e32 v74, v65
	v_lshlrev_b32_e32 v72, 16, v116
	v_and_b32_e32 v73, 0xffff0000, v116
	v_pk_mul_f32 v[72:73], v[74:75], v[72:73] op_sel_hi:[0,1]
	s_nop 0
	v_pk_mul_f32 v[72:73], v[220:221], v[72:73]
	s_nop 0
	v_cvt_pk_bf16_f32 v152, v72, v73
	v_lshlrev_b32_e32 v72, 16, v117
	v_and_b32_e32 v73, 0xffff0000, v117
	v_pk_mul_f32 v[72:73], v[74:75], v[72:73] op_sel_hi:[0,1]
	s_nop 0
	v_pk_mul_f32 v[72:73], v[222:223], v[72:73]
	s_nop 0
	v_cvt_pk_bf16_f32 v153, v72, v73
	v_lshlrev_b32_e32 v72, 16, v118
	v_and_b32_e32 v73, 0xffff0000, v118
	v_pk_mul_f32 v[72:73], v[74:75], v[72:73] op_sel_hi:[0,1]
	s_nop 0
	v_pk_mul_f32 v[72:73], v[148:149], v[72:73]
	s_nop 0
	v_cvt_pk_bf16_f32 v154, v72, v73
	v_lshlrev_b32_e32 v72, 16, v119
	v_and_b32_e32 v73, 0xffff0000, v119
	v_pk_mul_f32 v[72:73], v[74:75], v[72:73] op_sel_hi:[0,1]
	s_nop 0
	v_pk_mul_f32 v[72:73], v[150:151], v[72:73]
	s_nop 0
	v_cvt_pk_bf16_f32 v155, v72, v73
	global_store_dwordx4 v[34:35], v[152:155], off
	s_nop 1
	v_add_u32_e32 v31, 0x140, v36
	v_ashrrev_i32_e32 v34, 3, v31
	v_ashrrev_i32_e32 v35, 31, v34
	v_lshl_add_u64 v[34:35], v[32:33], 0, v[34:35]
	v_lshlrev_b64 v[34:35], 9, v[34:35]
	v_lshl_add_u64 v[34:35], v[8:9], 0, v[34:35]
	v_mov_b32_e32 v74, v66
	v_lshlrev_b32_e32 v72, 16, v120
	v_and_b32_e32 v73, 0xffff0000, v120
	v_pk_mul_f32 v[72:73], v[74:75], v[72:73] op_sel_hi:[0,1]
	s_nop 0
	v_pk_mul_f32 v[72:73], v[220:221], v[72:73]
	s_nop 0
	v_cvt_pk_bf16_f32 v152, v72, v73
	v_lshlrev_b32_e32 v72, 16, v121
	v_and_b32_e32 v73, 0xffff0000, v121
	v_pk_mul_f32 v[72:73], v[74:75], v[72:73] op_sel_hi:[0,1]
	s_nop 0
	v_pk_mul_f32 v[72:73], v[222:223], v[72:73]
	s_nop 0
	v_cvt_pk_bf16_f32 v153, v72, v73
	v_lshlrev_b32_e32 v72, 16, v122
	v_and_b32_e32 v73, 0xffff0000, v122
	v_pk_mul_f32 v[72:73], v[74:75], v[72:73] op_sel_hi:[0,1]
	s_nop 0
	v_pk_mul_f32 v[72:73], v[148:149], v[72:73]
	s_nop 0
	v_cvt_pk_bf16_f32 v154, v72, v73
	v_lshlrev_b32_e32 v72, 16, v123
	v_and_b32_e32 v73, 0xffff0000, v123
	v_pk_mul_f32 v[72:73], v[74:75], v[72:73] op_sel_hi:[0,1]
	s_nop 0
	v_pk_mul_f32 v[72:73], v[150:151], v[72:73]
	s_nop 0
	v_cvt_pk_bf16_f32 v155, v72, v73
	global_store_dwordx4 v[34:35], v[152:155], off
	s_nop 1
	v_add_u32_e32 v31, 0x160, v36
	v_ashrrev_i32_e32 v34, 3, v31
	v_ashrrev_i32_e32 v35, 31, v34
	v_lshl_add_u64 v[34:35], v[32:33], 0, v[34:35]
	v_lshlrev_b64 v[34:35], 9, v[34:35]
	v_lshl_add_u64 v[34:35], v[8:9], 0, v[34:35]
	v_mov_b32_e32 v74, v67
	v_lshlrev_b32_e32 v72, 16, v124
	v_and_b32_e32 v73, 0xffff0000, v124
	v_pk_mul_f32 v[72:73], v[74:75], v[72:73] op_sel_hi:[0,1]
	s_nop 0
	v_pk_mul_f32 v[72:73], v[220:221], v[72:73]
	s_nop 0
	v_cvt_pk_bf16_f32 v152, v72, v73
	v_lshlrev_b32_e32 v72, 16, v125
	v_and_b32_e32 v73, 0xffff0000, v125
	v_pk_mul_f32 v[72:73], v[74:75], v[72:73] op_sel_hi:[0,1]
	s_nop 0
	v_pk_mul_f32 v[72:73], v[222:223], v[72:73]
	s_nop 0
	v_cvt_pk_bf16_f32 v153, v72, v73
	v_lshlrev_b32_e32 v72, 16, v126
	v_and_b32_e32 v73, 0xffff0000, v126
	v_pk_mul_f32 v[72:73], v[74:75], v[72:73] op_sel_hi:[0,1]
	s_nop 0
	v_pk_mul_f32 v[72:73], v[148:149], v[72:73]
	s_nop 0
	v_cvt_pk_bf16_f32 v154, v72, v73
	v_lshlrev_b32_e32 v72, 16, v127
	v_and_b32_e32 v73, 0xffff0000, v127
	v_pk_mul_f32 v[72:73], v[74:75], v[72:73] op_sel_hi:[0,1]
	s_nop 0
	v_pk_mul_f32 v[72:73], v[150:151], v[72:73]
	s_nop 0
	v_cvt_pk_bf16_f32 v155, v72, v73
	global_store_dwordx4 v[34:35], v[152:155], off
	s_nop 1
	v_add_u32_e32 v31, 0x180, v36
	v_ashrrev_i32_e32 v34, 3, v31
	v_ashrrev_i32_e32 v35, 31, v34
	v_lshl_add_u64 v[34:35], v[32:33], 0, v[34:35]
	v_lshlrev_b64 v[34:35], 9, v[34:35]
	v_lshl_add_u64 v[34:35], v[8:9], 0, v[34:35]
	v_mov_b32_e32 v74, v68
	v_lshlrev_b32_e32 v72, 16, v128
	v_and_b32_e32 v73, 0xffff0000, v128
	v_pk_mul_f32 v[72:73], v[74:75], v[72:73] op_sel_hi:[0,1]
	s_nop 0
	v_pk_mul_f32 v[72:73], v[220:221], v[72:73]
	s_nop 0
	v_cvt_pk_bf16_f32 v152, v72, v73
	v_lshlrev_b32_e32 v72, 16, v129
	v_and_b32_e32 v73, 0xffff0000, v129
	v_pk_mul_f32 v[72:73], v[74:75], v[72:73] op_sel_hi:[0,1]
; __device__ __forceinline__ unsigned pk2(float lo, float hi) { f32x2_t v = {lo, hi}; bf16x2_hw b = __builtin_convertvector(v, bf16x2_hw); return __builtin_bit_cast(unsigned, b); }
; __device__ __forceinline__ void fox_prep(ArgsP a, int j, unsigned char* lds) {
;     ...
;             const float rs = rsqrtf(ss * (1.f / 128.f) + EPS_) * (which == 0 ? 0.12751743f : 1.f);
;             const float* nw = (which == 0 ? qnw : knw) + sub * 8;
;             u32x4 o;
; #pragma unroll
;             for (int e = 0; e < 4; ++e) o[e] = pk2(v[2 * e] * rs * nw[2 * e], v[2 * e + 1] * rs * nw[2 * e + 1]);
;             *(u32x4*)ptr = o; }
;         __syncthreads();
	s_nop 0
	v_pk_mul_f32 v[72:73], v[222:223], v[72:73]
	s_nop 0
	v_cvt_pk_bf16_f32 v153, v72, v73
	v_lshlrev_b32_e32 v72, 16, v130
	v_and_b32_e32 v73, 0xffff0000, v130
	v_pk_mul_f32 v[72:73], v[74:75], v[72:73] op_sel_hi:[0,1]
	s_nop 0
	v_pk_mul_f32 v[72:73], v[148:149], v[72:73]
	s_nop 0
	v_cvt_pk_bf16_f32 v154, v72, v73
	v_lshlrev_b32_e32 v72, 16, v131
	v_and_b32_e32 v73, 0xffff0000, v131
	v_pk_mul_f32 v[72:73], v[74:75], v[72:73] op_sel_hi:[0,1]
	s_nop 0
	v_pk_mul_f32 v[72:73], v[150:151], v[72:73]
	s_nop 0
	v_cvt_pk_bf16_f32 v155, v72, v73
	global_store_dwordx4 v[34:35], v[152:155], off
	s_nop 1
	v_add_u32_e32 v31, 0x1a0, v36
	v_ashrrev_i32_e32 v34, 3, v31
	v_ashrrev_i32_e32 v35, 31, v34
	v_lshl_add_u64 v[34:35], v[32:33], 0, v[34:35]
	v_lshlrev_b64 v[34:35], 9, v[34:35]
	v_lshl_add_u64 v[34:35], v[8:9], 0, v[34:35]
	v_mov_b32_e32 v74, v69
	v_lshlrev_b32_e32 v72, 16, v132
	v_and_b32_e32 v73, 0xffff0000, v132
	v_pk_mul_f32 v[72:73], v[74:75], v[72:73] op_sel_hi:[0,1]
	s_nop 0
	v_pk_mul_f32 v[72:73], v[220:221], v[72:73]
	s_nop 0
	v_cvt_pk_bf16_f32 v152, v72, v73
	v_lshlrev_b32_e32 v72, 16, v133
	v_and_b32_e32 v73, 0xffff0000, v133
	v_pk_mul_f32 v[72:73], v[74:75], v[72:73] op_sel_hi:[0,1]
	s_nop 0
	v_pk_mul_f32 v[72:73], v[222:223], v[72:73]
	s_nop 0
	v_cvt_pk_bf16_f32 v153, v72, v73
	v_lshlrev_b32_e32 v72, 16, v134
	v_and_b32_e32 v73, 0xffff0000, v134
	v_pk_mul_f32 v[72:73], v[74:75], v[72:73] op_sel_hi:[0,1]
	s_nop 0
	v_pk_mul_f32 v[72:73], v[148:149], v[72:73]
	s_nop 0
	v_cvt_pk_bf16_f32 v154, v72, v73
	v_lshlrev_b32_e32 v72, 16, v135
	v_and_b32_e32 v73, 0xffff0000, v135
	v_pk_mul_f32 v[72:73], v[74:75], v[72:73] op_sel_hi:[0,1]
	s_nop 0
	v_pk_mul_f32 v[72:73], v[150:151], v[72:73]
	s_nop 0
	v_cvt_pk_bf16_f32 v155, v72, v73
	global_store_dwordx4 v[34:35], v[152:155], off
	s_nop 1
	v_add_u32_e32 v31, 0x1c0, v36
	v_ashrrev_i32_e32 v34, 3, v31
	v_ashrrev_i32_e32 v35, 31, v34
	v_lshl_add_u64 v[34:35], v[32:33], 0, v[34:35]
	v_lshlrev_b64 v[34:35], 9, v[34:35]
	v_lshl_add_u64 v[34:35], v[8:9], 0, v[34:35]
	v_mov_b32_e32 v74, v70
	v_lshlrev_b32_e32 v72, 16, v136
	v_and_b32_e32 v73, 0xffff0000, v136
	v_pk_mul_f32 v[72:73], v[74:75], v[72:73] op_sel_hi:[0,1]
	s_nop 0
	v_pk_mul_f32 v[72:73], v[220:221], v[72:73]
	s_nop 0
	v_cvt_pk_bf16_f32 v152, v72, v73
	v_lshlrev_b32_e32 v72, 16, v137
	v_and_b32_e32 v73, 0xffff0000, v137
	v_pk_mul_f32 v[72:73], v[74:75], v[72:73] op_sel_hi:[0,1]
	s_nop 0
	v_pk_mul_f32 v[72:73], v[222:223], v[72:73]
	s_nop 0
	v_cvt_pk_bf16_f32 v153, v72, v73
	v_lshlrev_b32_e32 v72, 16, v138
	v_and_b32_e32 v73, 0xffff0000, v138
	v_pk_mul_f32 v[72:73], v[74:75], v[72:73] op_sel_hi:[0,1]
	s_nop 0
	v_pk_mul_f32 v[72:73], v[148:149], v[72:73]
	s_nop 0
	v_cvt_pk_bf16_f32 v154, v72, v73
	v_lshlrev_b32_e32 v72, 16, v139
	v_and_b32_e32 v73, 0xffff0000, v139
	v_pk_mul_f32 v[72:73], v[74:75], v[72:73] op_sel_hi:[0,1]
	s_nop 0
	v_pk_mul_f32 v[72:73], v[150:151], v[72:73]
	s_nop 0
	v_cvt_pk_bf16_f32 v155, v72, v73
	global_store_dwordx4 v[34:35], v[152:155], off
	s_nop 1
	v_add_u32_e32 v31, 0x1e0, v36
	v_ashrrev_i32_e32 v34, 3, v31
	v_ashrrev_i32_e32 v35, 31, v34
	v_lshl_add_u64 v[34:35], v[32:33], 0, v[34:35]
	v_lshlrev_b64 v[34:35], 9, v[34:35]
	v_lshl_add_u64 v[34:35], v[8:9], 0, v[34:35]
	v_mov_b32_e32 v74, v71
	v_lshlrev_b32_e32 v72, 16, v140
	v_and_b32_e32 v73, 0xffff0000, v140
	v_pk_mul_f32 v[72:73], v[74:75], v[72:73] op_sel_hi:[0,1]
	s_nop 0
	v_pk_mul_f32 v[72:73], v[220:221], v[72:73]
	s_nop 0
	v_cvt_pk_bf16_f32 v152, v72, v73
	v_lshlrev_b32_e32 v72, 16, v141
	v_and_b32_e32 v73, 0xffff0000, v141
	v_pk_mul_f32 v[72:73], v[74:75], v[72:73] op_sel_hi:[0,1]
	s_nop 0
	v_pk_mul_f32 v[72:73], v[222:223], v[72:73]
	s_nop 0
	v_cvt_pk_bf16_f32 v153, v72, v73
	v_lshlrev_b32_e32 v72, 16, v142
	v_and_b32_e32 v73, 0xffff0000, v142
	v_pk_mul_f32 v[72:73], v[74:75], v[72:73] op_sel_hi:[0,1]
	s_nop 0
	v_pk_mul_f32 v[72:73], v[148:149], v[72:73]
	s_nop 0
	v_cvt_pk_bf16_f32 v154, v72, v73
	v_lshlrev_b32_e32 v72, 16, v143
	v_and_b32_e32 v73, 0xffff0000, v143
	v_pk_mul_f32 v[72:73], v[74:75], v[72:73] op_sel_hi:[0,1]
	s_nop 0
	v_pk_mul_f32 v[72:73], v[150:151], v[72:73]
	s_nop 0
	v_cvt_pk_bf16_f32 v155, v72, v73
	global_store_dwordx4 v[34:35], v[152:155], off
	s_nop 1
	s_waitcnt lgkmcnt(0)
	s_lshl_b32 s68, s5, 1
	s_lshl_b32 s4, s4, 2
	v_lshl_add_u64 v[32:33], v[28:29], 0, s[68:69]
	s_mov_b32 s5, 0
	s_barrier
